# scan loaders allow six chunks in flight instead of nine (same lookahead)
# speedup vs baseline: 1.0247x; 1.0247x over previous
; #define SP_BAR() asm volatile("s_waitcnt lgkmcnt(0)\n\ts_barrier" ::: "memory")
; #define SP_WAIT() asm volatile("s_waitcnt vmcnt(36)" ::: "memory")
; __device__ __forceinline__ void p3_rwkv_state(Frame& F, const Args& a) {
;     ...
;     if (loader) {
;         DmaPtrs P; rw_dma_init(a, P, head, ib, lw, lane);
;         for (int n = 0; n < SP_D; ++n) rw_dma_issue(P, lw, lane, lds0 + (unsigned)(n % SP_R) * SP_SLOT);
;         SP_WAIT();
;         SP_BAR();
.Lscan_ldbig_pro:
	s_add_i32 s16, s15, s14
	s_mov_b32 m0, s16
	s_add_i32 s15, s15, 0x2800
	global_load_lds_dwordx4 v[2:3], off
	global_load_lds_dwordx4 v[2:3], off offset:1024
	s_cmp_eq_u32 s15, 0x25800
	s_cselect_b32 s15, 0, s15
	v_lshl_add_u64 v[2:3], v[2:3], 0, s[6:7]
	s_add_i32 s18, s18, 1
	s_cmp_lt_u32 s18, 12
	s_cbranch_scc1 .Lscan_ldbig_pro
	s_waitcnt vmcnt(12)
	s_barrier
	s_mov_b32 s18, 0
	s_movk_i32 s17, 0x100

; #define SP_BAR() asm volatile("s_waitcnt lgkmcnt(0)\n\ts_barrier" ::: "memory")
; #define SP_WAIT() asm volatile("s_waitcnt vmcnt(36)" ::: "memory")
; __device__ __forceinline__ void p3_rwkv_state(Frame& F, const Args& a) {
;     ...
;         for (int n = 0; n < NC; n += 2) {
;             if (n + SP_D + 1 < NC) { rw_dma_issue(P, lw, lane, lds0 + (unsigned)((n + SP_D) % SP_R) * SP_SLOT); rw_dma_issue(P, lw, lane, lds0 + (unsigned)((n + SP_D + 1) % SP_R) * SP_SLOT); SP_WAIT(); }
;             else asm volatile("s_waitcnt vmcnt(0)" ::: "memory");
;             SP_BAR();
.Lscan_ldbig_go:
	s_add_i32 s16, s15, s14
	s_mov_b32 m0, s16
	s_add_i32 s15, s15, 0x2800
	global_load_lds_dwordx4 v[2:3], off
	global_load_lds_dwordx4 v[2:3], off offset:1024
	s_cmp_eq_u32 s15, 0x25800
	s_cselect_b32 s15, 0, s15
	v_lshl_add_u64 v[2:3], v[2:3], 0, s[6:7]
	s_add_i32 s16, s15, s14
	s_mov_b32 m0, s16
	s_add_i32 s15, s15, 0x2800
	global_load_lds_dwordx4 v[2:3], off
	global_load_lds_dwordx4 v[2:3], off offset:1024
	s_cmp_eq_u32 s15, 0x25800
	s_cselect_b32 s15, 0, s15
	v_lshl_add_u64 v[2:3], v[2:3], 0, s[6:7]
	s_waitcnt vmcnt(12)
	s_branch .Lscan_ldbig_bar

; #define SP_BAR() asm volatile("s_waitcnt lgkmcnt(0)\n\ts_barrier" ::: "memory")
; #define SP_WAIT() asm volatile("s_waitcnt vmcnt(36)" ::: "memory")
; __device__ __forceinline__ void p3_rwkv_state(Frame& F, const Args& a) {
;     ...
;     if (loader) {
;         DmaPtrs P; rw_dma_init(a, P, head, ib, lw, lane);
;         for (int n = 0; n < SP_D; ++n) rw_dma_issue(P, lw, lane, lds0 + (unsigned)(n % SP_R) * SP_SLOT);
;         SP_WAIT();
;         SP_BAR();
.Lscan_ldsmall_pro:
	s_add_i32 s16, s15, 0x2000
	s_mov_b32 m0, s16
	s_mov_b32 exec_hi, 0
	s_add_i32 s15, s15, 0x2800
	global_load_lds_dwordx4 v[2:3], off
	global_load_lds_dwordx4 v[4:5], off offset:512
	global_load_lds_dwordx4 v[6:7], off offset:1024
	s_mov_b32 exec_lo, 0xffff
	s_cmp_eq_u32 s15, 0x25800
	global_load_lds_dwordx4 v[8:9], off offset:1536
	s_mov_b64 exec, -1
	s_cselect_b32 s15, 0, s15
	v_lshl_add_u64 v[2:3], v[2:3], 0, s[6:7]
	v_lshl_add_u64 v[4:5], v[4:5], 0, s[6:7]
	v_lshl_add_u64 v[6:7], v[6:7], 0, s[6:7]
	v_lshl_add_u64 v[8:9], v[8:9], 0, s[10:11]
	s_add_i32 s18, s18, 1
	s_cmp_lt_u32 s18, 12
	s_cbranch_scc1 .Lscan_ldsmall_pro
	s_waitcnt vmcnt(24)
	s_barrier
	s_mov_b32 s18, 0
	s_movk_i32 s17, 0x100

; #define SP_BAR() asm volatile("s_waitcnt lgkmcnt(0)\n\ts_barrier" ::: "memory")
; #define SP_WAIT() asm volatile("s_waitcnt vmcnt(36)" ::: "memory")
; __device__ __forceinline__ void p3_rwkv_state(Frame& F, const Args& a) {
;     ...
;         for (int n = 0; n < NC; n += 2) {
;             if (n + SP_D + 1 < NC) { rw_dma_issue(P, lw, lane, lds0 + (unsigned)((n + SP_D) % SP_R) * SP_SLOT); rw_dma_issue(P, lw, lane, lds0 + (unsigned)((n + SP_D + 1) % SP_R) * SP_SLOT); SP_WAIT(); }
;             else asm volatile("s_waitcnt vmcnt(0)" ::: "memory");
;             SP_BAR();
.Lscan_ldsmall_go:
	s_add_i32 s16, s15, 0x2000
	s_mov_b32 m0, s16
	s_mov_b32 exec_hi, 0
	s_add_i32 s15, s15, 0x2800
	global_load_lds_dwordx4 v[2:3], off
	global_load_lds_dwordx4 v[4:5], off offset:512
	global_load_lds_dwordx4 v[6:7], off offset:1024
	s_mov_b32 exec_lo, 0xffff
	s_cmp_eq_u32 s15, 0x25800
	global_load_lds_dwordx4 v[8:9], off offset:1536
	s_mov_b64 exec, -1
	s_cselect_b32 s15, 0, s15
	v_lshl_add_u64 v[2:3], v[2:3], 0, s[6:7]
	v_lshl_add_u64 v[4:5], v[4:5], 0, s[6:7]
	v_lshl_add_u64 v[6:7], v[6:7], 0, s[6:7]
	v_lshl_add_u64 v[8:9], v[8:9], 0, s[10:11]
	s_add_i32 s16, s15, 0x2000
	s_mov_b32 m0, s16
	s_mov_b32 exec_hi, 0
	s_add_i32 s15, s15, 0x2800
	global_load_lds_dwordx4 v[2:3], off
	global_load_lds_dwordx4 v[4:5], off offset:512
	global_load_lds_dwordx4 v[6:7], off offset:1024
	s_mov_b32 exec_lo, 0xffff
	s_cmp_eq_u32 s15, 0x25800
	global_load_lds_dwordx4 v[8:9], off offset:1536
	s_mov_b64 exec, -1
	s_cselect_b32 s15, 0, s15
	v_lshl_add_u64 v[2:3], v[2:3], 0, s[6:7]
	v_lshl_add_u64 v[4:5], v[4:5], 0, s[6:7]
	v_lshl_add_u64 v[6:7], v[6:7], 0, s[6:7]
	v_lshl_add_u64 v[8:9], v[8:9], 0, s[10:11]
	s_waitcnt vmcnt(24)
	s_branch .Lscan_ldsmall_bar
